# GEMM K-loop head aligned to 64 bytes (.p2align 6; pad nops run once per unit)
# baseline (speedup 1.0000x reference)
; #define PG8_STAGE(bufoff, gbase, voff) do { _Pragma("unroll") for (int _i = 0; _i < 2; ++_i) \
;         __builtin_amdgcn_global_load_lds((const unsigned*)((const char*)(gbase) + (voff)[_i]), (LAS unsigned*)(lds + (bufoff) + ldsw + _i * 8192), 16, 0, 0); } while (0)
; #define PG8_LDA(dst, b, h) do { _Pragma("unroll") for (int m = 0; m < 4; ++m) _Pragma("unroll") for (int k = 0; k < 2; ++k) dst[m][k] = *(const LAS bf16x8*)(lds + PG8_SA(b, h) + aoff + m * 2048 + k * 1024); } while (0)
; #define PG8_LDB(dst, b, h) do { _Pragma("unroll") for (int n = 0; n < 2; ++n) _Pragma("unroll") for (int k = 0; k < 2; ++k) dst[n][k] = *(const LAS bf16x8*)(lds + PG8_SB(b, h) + boff + n * 2048 + k * 1024); } while (0)
; #define PG8_MMA(ai, bj, At, Bt) do { __builtin_amdgcn_s_setprio(1); _Pragma("unroll") for (int m = 0; m < 4; ++m) _Pragma("unroll") for (int n = 0; n < 2; ++n) _Pragma("unroll") for (int k = 0; k < 2; ++k) \
;         acc[ai][bj][m][n] = __builtin_amdgcn_mfma_f32_16x16x32_bf16(Bt[n][k], At[m][k], acc[ai][bj][m][n], 0, 0, 0); __builtin_amdgcn_s_setprio(0); } while (0)
; #define PG8_WAIT_V(n) asm volatile("s_waitcnt vmcnt(" #n ")" ::: "memory")
; #define PG8_WAIT_L(n) asm volatile("s_waitcnt lgkmcnt(" #n ")" ::: "memory")
; #define PG8_BAR __builtin_amdgcn_s_barrier()
; #define PG8_SCHED __builtin_amdgcn_sched_barrier(0)
; __device__ __forceinline__ void gemm_phase(LAS unsigned char* lds, const GemmP g, const EpiP e) {
;     ...
;         for (int t = 0; t < nt; t += 2) {
;             const bool last = (t == nt - 2);
;             const char* a1 = cA + (size_t)(t + 1) * kstepA;
;             const char* a2 = last ? nA : cA + (size_t)(t + 2) * kstepA; const char* b2 = last ? nB : cB + (size_t)(t + 2) * kstepB;
;             const char* a3 = a2 + kstepA; const char* b3 = b2 + kstepB;
;             PG8_LDB(B0, 0, 0); PG8_LDB(B1, 0, 1); PG8_SCHED; PG8_LDA(At, 0, 0); PG8_STAGE(PG8_SA(1, 1), a1 + hstepA, voffA);
;             PG8_WAIT_V(8); PG8_WAIT_L(0); PG8_BAR; PG8_MMA(0, 0, At, B0); PG8_MMA(0, 1, At, B1); PG8_BAR; PG8_SCHED;
;             PG8_LDA(At, 0, 1); PG8_STAGE(PG8_SB(0, 0), b2, voffB); PG8_STAGE(PG8_SB(0, 1), b2 + hstepB, voffB); PG8_STAGE(PG8_SA(0, 0), a2, voffA);
;             PG8_WAIT_V(8); PG8_WAIT_L(0); PG8_BAR; PG8_MMA(1, 0, At, B0); PG8_MMA(1, 1, At, B1); PG8_BAR; PG8_SCHED;
.LBB0_392:
	s_cmp_lt_i32 s69, 1
	s_cbranch_scc1 .LBB0_395
	s_add_u32 s24, s78, s90
	s_addc_u32 s25, s79, s7
	s_add_i32 s26, s69, -2
	s_add_u32 s27, s40, 0x100
	s_addc_u32 s28, s41, 0
	s_mov_b64 s[18:19], 0
	s_cmp_eq_u32 s99, 0
	s_cbranch_scc1 .LBB0_394
	s_mov_b32 s99, 0
	s_add_u32 s30, s18, 1
	s_addc_u32 s31, s19, 0
	s_add_u32 s16, s18, 2
	s_addc_u32 s17, s19, 0
	s_lshl_b64 s[20:21], s[16:17], s77
	s_add_u32 s19, s78, s20
	s_addc_u32 s20, s79, s21
	s_cmp_eq_u32 s26, s18
	s_cselect_b32 s21, s51, s20
	s_cselect_b32 s20, s50, s19
	s_cselect_b32 s22, s80, s27
	s_cselect_b32 s23, s81, s28
	s_add_u32 s18, s20, s38
	s_addc_u32 s19, s21, s39
	s_add_i32 s29, 0, 0x10000
	v_add_u32_e32 v96, s29, v179
	s_add_i32 s34, 0, 0x14000
	ds_read_b128 v[132:135], v96
	ds_read_b128 v[136:139], v96 offset:1024
	ds_read_b128 v[160:163], v96 offset:2048
	ds_read_b128 v[164:167], v96 offset:3072
	v_add_u32_e32 v96, s34, v179
	ds_read_b128 v[168:171], v96
	ds_read_b128 v[172:175], v96 offset:1024
	ds_read_b128 v[216:219], v96 offset:2048
	ds_read_b128 v[220:223], v96 offset:3072
	s_lshl_b64 s[30:31], s[30:31], s77
	s_add_u32 s30, s24, s30
	s_addc_u32 s31, s25, s31
	v_lshl_add_u64 v[98:99], s[30:31], 0, v[140:141]
	s_add_i32 m0, s92, 0xc000
	ds_read_b128 v[224:227], v188
	ds_read_b128 v[228:231], v188 offset:1024
	ds_read_b128 v[232:235], v188 offset:2048
	ds_read_b128 v[236:239], v188 offset:3072
	ds_read_b128 v[240:243], v188 offset:4096
	ds_read_b128 v[244:247], v188 offset:5120
	ds_read_b128 v[248:251], v188 offset:6144
	ds_read_b128 v[204:207], v188 offset:7168
	global_load_lds_dwordx4 v[98:99], off
	v_lshl_add_u64 v[98:99], s[30:31], 0, v[142:143]
	s_add_i32 m0, s92, 0xe000
	s_nop 0
	global_load_lds_dwordx4 v[98:99], off
	s_waitcnt vmcnt(24)
	s_waitcnt lgkmcnt(0)
	s_barrier
	s_setprio 1
	s_waitcnt lgkmcnt(0)
	v_mfma_f32_16x16x32_bf16 v[128:131], v[132:135], v[224:227], v[128:131]
	v_mfma_f32_16x16x32_bf16 v[124:127], v[160:163], v[224:227], v[124:127]
	v_mfma_f32_16x16x32_bf16 v[120:123], v[132:135], v[232:235], v[120:123]
	v_mfma_f32_16x16x32_bf16 v[116:119], v[160:163], v[232:235], v[116:119]
	v_mfma_f32_16x16x32_bf16 v[112:115], v[132:135], v[240:243], v[112:115]
	v_mfma_f32_16x16x32_bf16 v[108:111], v[160:163], v[240:243], v[108:111]
	v_mfma_f32_16x16x32_bf16 v[104:107], v[132:135], v[248:251], v[104:107]
	v_mfma_f32_16x16x32_bf16 v[98:101], v[160:163], v[248:251], v[100:103]
	v_mfma_f32_16x16x32_bf16 v[128:131], v[136:139], v[228:231], v[128:131]
	v_mfma_f32_16x16x32_bf16 v[124:127], v[164:167], v[228:231], v[124:127]
	v_mfma_f32_16x16x32_bf16 v[120:123], v[136:139], v[236:239], v[120:123]
	v_mfma_f32_16x16x32_bf16 v[116:119], v[164:167], v[236:239], v[116:119]
	v_mfma_f32_16x16x32_bf16 v[112:115], v[136:139], v[244:247], v[112:115]
	v_mfma_f32_16x16x32_bf16 v[108:111], v[164:167], v[244:247], v[108:111]
	v_mfma_f32_16x16x32_bf16 v[104:107], v[136:139], v[204:207], v[104:107]
	v_mfma_f32_16x16x32_bf16 v[98:101], v[164:167], v[204:207], v[98:101]
	s_setprio 0
	s_setprio 1
	v_mfma_f32_16x16x32_bf16 v[92:95], v[168:171], v[224:227], v[92:95]
	v_mfma_f32_16x16x32_bf16 v[88:91], v[216:219], v[224:227], v[88:91]
	v_mfma_f32_16x16x32_bf16 v[84:87], v[168:171], v[232:235], v[84:87]
	v_mfma_f32_16x16x32_bf16 v[80:83], v[216:219], v[232:235], v[80:83]
	v_mfma_f32_16x16x32_bf16 v[76:79], v[168:171], v[240:243], v[76:79]
	v_mfma_f32_16x16x32_bf16 v[72:75], v[216:219], v[240:243], v[72:75]
	v_mfma_f32_16x16x32_bf16 v[68:71], v[168:171], v[248:251], v[68:71]
	v_mfma_f32_16x16x32_bf16 v[64:67], v[216:219], v[248:251], v[64:67]
	v_mfma_f32_16x16x32_bf16 v[92:95], v[172:175], v[228:231], v[92:95]
	v_mfma_f32_16x16x32_bf16 v[88:91], v[220:223], v[228:231], v[88:91]
	v_mfma_f32_16x16x32_bf16 v[84:87], v[172:175], v[236:239], v[84:87]
	v_mfma_f32_16x16x32_bf16 v[80:83], v[220:223], v[236:239], v[80:83]
	v_mfma_f32_16x16x32_bf16 v[76:79], v[172:175], v[244:247], v[76:79]
	v_mfma_f32_16x16x32_bf16 v[72:75], v[220:223], v[244:247], v[72:75]
	v_mfma_f32_16x16x32_bf16 v[68:71], v[172:175], v[204:207], v[68:71]
	v_mfma_f32_16x16x32_bf16 v[64:67], v[220:223], v[204:207], v[64:67]
	s_setprio 0
	s_barrier
	s_add_i32 s29, s29, s91
	v_lshl_add_u64 v[176:177], s[22:23], 0, v[146:147]
	s_mov_b32 m0, s29
	ds_read_b128 v[204:207], v188 offset:16384
	ds_read_b128 v[224:227], v188 offset:17408
	ds_read_b128 v[228:231], v188 offset:18432
	ds_read_b128 v[232:235], v188 offset:19456
	ds_read_b128 v[236:239], v188 offset:20480
	ds_read_b128 v[240:243], v188 offset:21504
	ds_read_b128 v[244:247], v188 offset:22528
	ds_read_b128 v[248:251], v188 offset:23552
	global_load_lds_dwordx4 v[176:177], off
	s_add_i32 m0, s29, 0x2000
	v_lshl_add_u64 v[210:211], s[22:23], 0, v[144:145]
	s_add_u32 s22, s22, s48
	s_addc_u32 s23, s23, s49
	s_add_i32 s29, s34, s91
	global_load_lds_dwordx4 v[210:211], off
	v_lshl_add_u64 v[212:213], s[22:23], 0, v[146:147]
	s_mov_b32 m0, s29
	v_lshl_add_u64 v[190:191], s[22:23], 0, v[144:145]
	global_load_lds_dwordx4 v[212:213], off
	s_add_i32 m0, s29, 0x2000
	v_lshl_add_u64 v[102:103], s[20:21], 0, v[140:141]
	global_load_lds_dwordx4 v[190:191], off
	s_mov_b32 m0, s92
	s_nop 0
	global_load_lds_dwordx4 v[102:103], off
	v_lshl_add_u64 v[102:103], s[20:21], 0, v[142:143]
	s_mov_b32 m0, s93
	s_nop 0
	global_load_lds_dwordx4 v[102:103], off
	s_waitcnt vmcnt(24)
	s_waitcnt lgkmcnt(0)
	s_barrier
; #define PG8_STAGE(bufoff, gbase, voff) do { _Pragma("unroll") for (int _i = 0; _i < 2; ++_i) \
;         __builtin_amdgcn_global_load_lds((const unsigned*)((const char*)(gbase) + (voff)[_i]), (LAS unsigned*)(lds + (bufoff) + ldsw + _i * 8192), 16, 0, 0); } while (0)
; #define PG8_LDA(dst, b, h) do { _Pragma("unroll") for (int m = 0; m < 4; ++m) _Pragma("unroll") for (int k = 0; k < 2; ++k) dst[m][k] = *(const LAS bf16x8*)(lds + PG8_SA(b, h) + aoff + m * 2048 + k * 1024); } while (0)
; #define PG8_LDB(dst, b, h) do { _Pragma("unroll") for (int n = 0; n < 2; ++n) _Pragma("unroll") for (int k = 0; k < 2; ++k) dst[n][k] = *(const LAS bf16x8*)(lds + PG8_SB(b, h) + boff + n * 2048 + k * 1024); } while (0)
; #define PG8_MMA(ai, bj, At, Bt) do { __builtin_amdgcn_s_setprio(1); _Pragma("unroll") for (int m = 0; m < 4; ++m) _Pragma("unroll") for (int n = 0; n < 2; ++n) _Pragma("unroll") for (int k = 0; k < 2; ++k) \
;         acc[ai][bj][m][n] = __builtin_amdgcn_mfma_f32_16x16x32_bf16(Bt[n][k], At[m][k], acc[ai][bj][m][n], 0, 0, 0); __builtin_amdgcn_s_setprio(0); } while (0)
; #define PG8_WAIT_V(n) asm volatile("s_waitcnt vmcnt(" #n ")" ::: "memory")
; #define PG8_WAIT_L(n) asm volatile("s_waitcnt lgkmcnt(" #n ")" ::: "memory")
; #define PG8_BAR __builtin_amdgcn_s_barrier()
; #define PG8_SCHED __builtin_amdgcn_sched_barrier(0)
; __device__ __forceinline__ void gemm_phase(LAS unsigned char* lds, const GemmP g, const EpiP e) {
;     ...
;             PG8_WAIT_V(8); PG8_WAIT_L(0); PG8_BAR; PG8_MMA(1, 0, At, B0); PG8_MMA(1, 1, At, B1); PG8_BAR; PG8_SCHED;
;             PG8_LDB(B0, 1, 0); PG8_LDB(B1, 1, 1); PG8_SCHED; PG8_LDA(At, 1, 0); PG8_STAGE(PG8_SA(0, 1), a2 + hstepA, voffA);
;             PG8_WAIT_V(8); PG8_WAIT_L(0); PG8_BAR; PG8_MMA(0, 0, At, B0); PG8_MMA(0, 1, At, B1); PG8_BAR; PG8_SCHED;
	s_setprio 1
	s_waitcnt lgkmcnt(0)
	v_mfma_f32_16x16x32_bf16 v[60:63], v[132:135], v[204:207], v[60:63]
	v_mfma_f32_16x16x32_bf16 v[56:59], v[160:163], v[204:207], v[56:59]
	v_mfma_f32_16x16x32_bf16 v[52:55], v[132:135], v[228:231], v[52:55]
	v_mfma_f32_16x16x32_bf16 v[48:51], v[160:163], v[228:231], v[48:51]
	v_mfma_f32_16x16x32_bf16 v[44:47], v[132:135], v[236:239], v[44:47]
	v_mfma_f32_16x16x32_bf16 v[40:43], v[160:163], v[236:239], v[40:43]
	v_mfma_f32_16x16x32_bf16 v[36:39], v[132:135], v[244:247], v[36:39]
	v_mfma_f32_16x16x32_bf16 v[32:35], v[160:163], v[244:247], v[32:35]
	v_mfma_f32_16x16x32_bf16 v[60:63], v[136:139], v[224:227], v[60:63]
	v_mfma_f32_16x16x32_bf16 v[56:59], v[164:167], v[224:227], v[56:59]
	v_mfma_f32_16x16x32_bf16 v[52:55], v[136:139], v[232:235], v[52:55]
	v_mfma_f32_16x16x32_bf16 v[48:51], v[164:167], v[232:235], v[48:51]
	v_mfma_f32_16x16x32_bf16 v[44:47], v[136:139], v[240:243], v[44:47]
	v_mfma_f32_16x16x32_bf16 v[40:43], v[164:167], v[240:243], v[40:43]
	v_mfma_f32_16x16x32_bf16 v[36:39], v[136:139], v[248:251], v[36:39]
	v_mfma_f32_16x16x32_bf16 v[32:35], v[164:167], v[248:251], v[32:35]
	s_setprio 0
	s_setprio 1
	v_mfma_f32_16x16x32_bf16 v[28:31], v[168:171], v[204:207], v[28:31]
	v_mfma_f32_16x16x32_bf16 v[24:27], v[216:219], v[204:207], v[24:27]
	v_mfma_f32_16x16x32_bf16 v[20:23], v[168:171], v[228:231], v[20:23]
	v_mfma_f32_16x16x32_bf16 v[16:19], v[216:219], v[228:231], v[16:19]
	v_mfma_f32_16x16x32_bf16 v[12:15], v[168:171], v[236:239], v[12:15]
	v_mfma_f32_16x16x32_bf16 v[8:11], v[216:219], v[236:239], v[8:11]
	v_mfma_f32_16x16x32_bf16 v[4:7], v[168:171], v[244:247], v[4:7]
	v_mfma_f32_16x16x32_bf16 v[0:3], v[216:219], v[244:247], v[0:3]
	v_mfma_f32_16x16x32_bf16 v[28:31], v[172:175], v[224:227], v[28:31]
	v_mfma_f32_16x16x32_bf16 v[24:27], v[220:223], v[224:227], v[24:27]
	v_mfma_f32_16x16x32_bf16 v[20:23], v[172:175], v[232:235], v[20:23]
	v_mfma_f32_16x16x32_bf16 v[16:19], v[220:223], v[232:235], v[16:19]
	v_mfma_f32_16x16x32_bf16 v[12:15], v[172:175], v[240:243], v[12:15]
	v_mfma_f32_16x16x32_bf16 v[8:11], v[220:223], v[240:243], v[8:11]
	v_mfma_f32_16x16x32_bf16 v[4:7], v[172:175], v[248:251], v[4:7]
	v_mfma_f32_16x16x32_bf16 v[0:3], v[220:223], v[248:251], v[0:3]
	s_setprio 0
	s_barrier
	s_add_i32 s22, 0, 0x18000
	v_add_u32_e32 v96, s22, v179
	s_add_i32 s23, 0, 0x1c000
	ds_read_b128 v[132:135], v96
	ds_read_b128 v[136:139], v96 offset:1024
	ds_read_b128 v[160:163], v96 offset:2048
	ds_read_b128 v[164:167], v96 offset:3072
	v_add_u32_e32 v96, s23, v179
	ds_read_b128 v[168:171], v96
	ds_read_b128 v[172:175], v96 offset:1024
	ds_read_b128 v[204:207], v96 offset:2048
	ds_read_b128 v[216:219], v96 offset:3072
	s_add_u32 s20, s20, s90
	s_addc_u32 s21, s21, s7
	s_mov_b32 m0, s73
	v_lshl_add_u64 v[102:103], s[20:21], 0, v[140:141]
	ds_read_b128 v[220:223], v188 offset:32768
	ds_read_b128 v[224:227], v188 offset:33792
	ds_read_b128 v[228:231], v188 offset:34816
	ds_read_b128 v[232:235], v188 offset:35840
	ds_read_b128 v[236:239], v188 offset:36864
	ds_read_b128 v[240:243], v188 offset:37888
	ds_read_b128 v[244:247], v188 offset:38912
	ds_read_b128 v[248:251], v188 offset:39936
	global_load_lds_dwordx4 v[102:103], off
	v_lshl_add_u64 v[102:103], s[20:21], 0, v[142:143]
	s_mov_b32 m0, s4
	s_nop 0
	global_load_lds_dwordx4 v[102:103], off
	s_waitcnt vmcnt(8)
	s_waitcnt lgkmcnt(0)
	s_barrier
	s_setprio 1
	s_waitcnt lgkmcnt(0)
	v_mfma_f32_16x16x32_bf16 v[128:131], v[132:135], v[220:223], v[128:131]
	v_mfma_f32_16x16x32_bf16 v[124:127], v[160:163], v[220:223], v[124:127]
	v_mfma_f32_16x16x32_bf16 v[120:123], v[132:135], v[228:231], v[120:123]
	v_mfma_f32_16x16x32_bf16 v[116:119], v[160:163], v[228:231], v[116:119]
	v_mfma_f32_16x16x32_bf16 v[112:115], v[132:135], v[236:239], v[112:115]
	v_mfma_f32_16x16x32_bf16 v[108:111], v[160:163], v[236:239], v[108:111]
	v_mfma_f32_16x16x32_bf16 v[102:105], v[132:135], v[244:247], v[104:107]
	v_mfma_f32_16x16x32_bf16 v[98:101], v[160:163], v[244:247], v[98:101]
	v_mfma_f32_16x16x32_bf16 v[128:131], v[136:139], v[224:227], v[128:131]
	v_mfma_f32_16x16x32_bf16 v[124:127], v[164:167], v[224:227], v[124:127]
	v_mfma_f32_16x16x32_bf16 v[120:123], v[136:139], v[232:235], v[120:123]
	v_mfma_f32_16x16x32_bf16 v[116:119], v[164:167], v[232:235], v[116:119]
	v_mfma_f32_16x16x32_bf16 v[112:115], v[136:139], v[240:243], v[112:115]
	v_mfma_f32_16x16x32_bf16 v[108:111], v[164:167], v[240:243], v[108:111]
	v_mfma_f32_16x16x32_bf16 v[104:107], v[136:139], v[248:251], v[102:105]
	v_mfma_f32_16x16x32_bf16 v[100:103], v[164:167], v[248:251], v[98:101]
	s_setprio 0
	s_setprio 1
	v_mfma_f32_16x16x32_bf16 v[92:95], v[168:171], v[220:223], v[92:95]
	v_mfma_f32_16x16x32_bf16 v[88:91], v[204:207], v[220:223], v[88:91]
	v_mfma_f32_16x16x32_bf16 v[84:87], v[168:171], v[228:231], v[84:87]
	v_mfma_f32_16x16x32_bf16 v[80:83], v[204:207], v[228:231], v[80:83]
	v_mfma_f32_16x16x32_bf16 v[76:79], v[168:171], v[236:239], v[76:79]
	v_mfma_f32_16x16x32_bf16 v[72:75], v[204:207], v[236:239], v[72:75]
	v_mfma_f32_16x16x32_bf16 v[68:71], v[168:171], v[244:247], v[68:71]
	v_mfma_f32_16x16x32_bf16 v[64:67], v[204:207], v[244:247], v[64:67]
	v_mfma_f32_16x16x32_bf16 v[92:95], v[172:175], v[224:227], v[92:95]
	v_mfma_f32_16x16x32_bf16 v[88:91], v[216:219], v[224:227], v[88:91]
	v_mfma_f32_16x16x32_bf16 v[84:87], v[172:175], v[232:235], v[84:87]
	v_mfma_f32_16x16x32_bf16 v[80:83], v[216:219], v[232:235], v[80:83]
	v_mfma_f32_16x16x32_bf16 v[76:79], v[172:175], v[240:243], v[76:79]
	v_mfma_f32_16x16x32_bf16 v[72:75], v[216:219], v[240:243], v[72:75]
	v_mfma_f32_16x16x32_bf16 v[68:71], v[172:175], v[248:251], v[68:71]
	v_mfma_f32_16x16x32_bf16 v[64:67], v[216:219], v[248:251], v[64:67]
	s_setprio 0
	s_barrier
; #define PG8_STAGE(bufoff, gbase, voff) do { _Pragma("unroll") for (int _i = 0; _i < 2; ++_i) \
;         __builtin_amdgcn_global_load_lds((const unsigned*)((const char*)(gbase) + (voff)[_i]), (LAS unsigned*)(lds + (bufoff) + ldsw + _i * 8192), 16, 0, 0); } while (0)
; #define PG8_LDA(dst, b, h) do { _Pragma("unroll") for (int m = 0; m < 4; ++m) _Pragma("unroll") for (int k = 0; k < 2; ++k) dst[m][k] = *(const LAS bf16x8*)(lds + PG8_SA(b, h) + aoff + m * 2048 + k * 1024); } while (0)
; #define PG8_MMA(ai, bj, At, Bt) do { __builtin_amdgcn_s_setprio(1); _Pragma("unroll") for (int m = 0; m < 4; ++m) _Pragma("unroll") for (int n = 0; n < 2; ++n) _Pragma("unroll") for (int k = 0; k < 2; ++k) \
;         acc[ai][bj][m][n] = __builtin_amdgcn_mfma_f32_16x16x32_bf16(Bt[n][k], At[m][k], acc[ai][bj][m][n], 0, 0, 0); __builtin_amdgcn_s_setprio(0); } while (0)
; #define PG8_WAIT_V(n) asm volatile("s_waitcnt vmcnt(" #n ")" ::: "memory")
; #define PG8_WAIT_L(n) asm volatile("s_waitcnt lgkmcnt(" #n ")" ::: "memory")
; #define PG8_BAR __builtin_amdgcn_s_barrier()
; #define PG8_SCHED __builtin_amdgcn_sched_barrier(0)
; __device__ __forceinline__ void gemm_phase(LAS unsigned char* lds, const GemmP g, const EpiP e) {
;     ...
;             PG8_LDA(At, 1, 1); PG8_STAGE(PG8_SB(1, 0), b3, voffB); PG8_STAGE(PG8_SB(1, 1), b3 + hstepB, voffB); PG8_STAGE(PG8_SA(1, 0), a3, voffA);
;             PG8_WAIT_V(8); PG8_WAIT_L(0); PG8_BAR; PG8_MMA(1, 0, At, B0); PG8_MMA(1, 1, At, B1); PG8_BAR; PG8_SCHED;
;         }
	s_add_i32 s20, s22, s91
	v_lshl_add_u64 v[98:99], v[176:177], 0, s[96:97]
	s_mov_b32 m0, s20
	ds_read_b128 v[220:223], v188 offset:49152
	ds_read_b128 v[224:227], v188 offset:50176
	ds_read_b128 v[228:231], v188 offset:51200
	ds_read_b128 v[232:235], v188 offset:52224
	ds_read_b128 v[236:239], v188 offset:53248
	ds_read_b128 v[240:243], v188 offset:54272
	ds_read_b128 v[244:247], v188 offset:55296
	ds_read_b128 v[248:251], v188 offset:56320
	global_load_lds_dwordx4 v[98:99], off
	v_lshl_add_u64 v[98:99], v[210:211], 0, s[96:97]
	s_add_i32 m0, s20, 0x2000
	s_add_i32 s20, s23, s91
	global_load_lds_dwordx4 v[98:99], off
	v_lshl_add_u64 v[98:99], v[212:213], 0, s[96:97]
	s_mov_b32 m0, s20
	s_nop 0
	global_load_lds_dwordx4 v[98:99], off
	v_lshl_add_u64 v[98:99], v[190:191], 0, s[96:97]
	s_add_i32 m0, s20, 0x2000
	s_nop 0
	global_load_lds_dwordx4 v[98:99], off
	v_lshl_add_u64 v[98:99], s[18:19], 0, v[140:141]
	s_mov_b32 m0, s5
	s_nop 0
	global_load_lds_dwordx4 v[98:99], off
	v_lshl_add_u64 v[98:99], s[18:19], 0, v[142:143]
	s_mov_b32 m0, s44
	s_nop 0
	global_load_lds_dwordx4 v[98:99], off
	s_waitcnt vmcnt(8)
	s_waitcnt lgkmcnt(0)
	s_barrier
	s_setprio 1
	s_waitcnt lgkmcnt(0)
	v_mfma_f32_16x16x32_bf16 v[60:63], v[132:135], v[220:223], v[60:63]
	v_mfma_f32_16x16x32_bf16 v[56:59], v[160:163], v[220:223], v[56:59]
	v_mfma_f32_16x16x32_bf16 v[52:55], v[132:135], v[228:231], v[52:55]
	v_mfma_f32_16x16x32_bf16 v[48:51], v[160:163], v[228:231], v[48:51]
	v_mfma_f32_16x16x32_bf16 v[44:47], v[132:135], v[236:239], v[44:47]
	v_mfma_f32_16x16x32_bf16 v[40:43], v[160:163], v[236:239], v[40:43]
	v_mfma_f32_16x16x32_bf16 v[36:39], v[132:135], v[244:247], v[36:39]
	v_mfma_f32_16x16x32_bf16 v[32:35], v[160:163], v[244:247], v[32:35]
	v_mfma_f32_16x16x32_bf16 v[60:63], v[136:139], v[224:227], v[60:63]
	v_mfma_f32_16x16x32_bf16 v[56:59], v[164:167], v[224:227], v[56:59]
	v_mfma_f32_16x16x32_bf16 v[52:55], v[136:139], v[232:235], v[52:55]
	v_mfma_f32_16x16x32_bf16 v[48:51], v[164:167], v[232:235], v[48:51]
	v_mfma_f32_16x16x32_bf16 v[44:47], v[136:139], v[240:243], v[44:47]
	v_mfma_f32_16x16x32_bf16 v[40:43], v[164:167], v[240:243], v[40:43]
	v_mfma_f32_16x16x32_bf16 v[36:39], v[136:139], v[248:251], v[36:39]
	v_mfma_f32_16x16x32_bf16 v[32:35], v[164:167], v[248:251], v[32:35]
	s_setprio 0
	s_setprio 1
	v_mfma_f32_16x16x32_bf16 v[28:31], v[168:171], v[220:223], v[28:31]
	v_mfma_f32_16x16x32_bf16 v[24:27], v[204:207], v[220:223], v[24:27]
	v_mfma_f32_16x16x32_bf16 v[20:23], v[168:171], v[228:231], v[20:23]
	v_mfma_f32_16x16x32_bf16 v[16:19], v[204:207], v[228:231], v[16:19]
	v_mfma_f32_16x16x32_bf16 v[12:15], v[168:171], v[236:239], v[12:15]
	v_mfma_f32_16x16x32_bf16 v[8:11], v[204:207], v[236:239], v[8:11]
	v_mfma_f32_16x16x32_bf16 v[4:7], v[168:171], v[244:247], v[4:7]
	v_mfma_f32_16x16x32_bf16 v[0:3], v[204:207], v[244:247], v[0:3]
	v_mfma_f32_16x16x32_bf16 v[28:31], v[172:175], v[224:227], v[28:31]
	v_mfma_f32_16x16x32_bf16 v[24:27], v[216:219], v[224:227], v[24:27]
	v_mfma_f32_16x16x32_bf16 v[20:23], v[172:175], v[232:235], v[20:23]
	v_mfma_f32_16x16x32_bf16 v[16:19], v[216:219], v[232:235], v[16:19]
	v_mfma_f32_16x16x32_bf16 v[12:15], v[172:175], v[240:243], v[12:15]
	v_mfma_f32_16x16x32_bf16 v[8:11], v[216:219], v[240:243], v[8:11]
	v_mfma_f32_16x16x32_bf16 v[4:7], v[172:175], v[248:251], v[4:7]
	v_mfma_f32_16x16x32_bf16 v[0:3], v[216:219], v[248:251], v[0:3]
	s_setprio 0
	s_barrier
	s_add_u32 s27, s27, 0x100
	s_addc_u32 s28, s28, 0
	s_cmp_ge_i32 s16, s69
	s_mov_b64 s[18:19], s[16:17]
	s_cbranch_scc0 .LBB0_394
	s_branch .LBB0_395
	.p2align 6
